# attention items handed out by 8 XCD-local queues (grid-row bands per XCD for L2 locality) with work stealing, instead of one global counter
# speedup vs baseline: 1.0002x; 1.0002x over previous
.LBB0_192:
	s_mov_b64 s[0:1], exec
	v_readlane_b32 s2, v255, 27
	v_readlane_b32 s3, v255, 28
	s_and_b64 s[2:3], s[0:1], s[2:3]
	s_mov_b64 exec, s[2:3]
	s_cbranch_execz .LBB0_196
	s_getreg_b32 s3, hwreg(HW_REG_XCC_ID, 0, 4)
	s_and_b32 s3, s3, 7
	v_readlane_b32 s6, v255, 25
	v_readlane_b32 s7, v255, 26
	v_readlane_b32 s36, v255, 11
	v_readlane_b32 s37, v254, 25
	s_mov_b32 s39, 0
	s_mov_b32 s4, 8
	s_nop 4
.Lq_try_a:
	s_lshr_b32 s5, s39, s3
	s_and_b32 s5, s5, 1
	s_cmp_eq_u32 s5, 1
	s_cbranch_scc1 .Lq_next_a
	s_lshl_b32 s5, s3, 2
	v_mov_b32_e32 v0, s5
	v_mov_b32_e32 v1, 1
	global_atomic_add v1, v0, v1, s[6:7] offset:64 sc0
	s_waitcnt vmcnt(0)
	v_readfirstlane_b32 s5, v1
	s_nop 3
	s_cmp_lt_u32 s5, s36
	s_cbranch_scc1 .Lq_got_a
	s_lshl_b32 s5, 1, s3
	s_or_b32 s39, s39, s5
.Lq_next_a:
	s_add_i32 s3, s3, 1
	s_and_b32 s3, s3, 7
	s_add_i32 s4, s4, -1
	s_cmp_lg_u32 s4, 0
	s_cbranch_scc1 .Lq_try_a
	s_mov_b32 s5, s37
	s_branch .Lq_done_a
.Lq_got_a:
	s_cmp_lt_u32 s5, 0x80
	s_cbranch_scc0 .Lq_ctx_a
	s_lshr_b32 s38, s5, 4
	s_bfe_u32 s4, s5, 0x30001
	s_lshl_b32 s3, s3, 3
	s_add_i32 s4, s4, s3
	s_lshl_b32 s4, s4, 1
	s_and_b32 s5, s5, 1
	s_add_i32 s5, s5, s4
	s_mul_i32 s38, s38, s36
	s_add_i32 s5, s5, s38
	s_branch .Lq_done_a
.Lq_ctx_a:
	s_mul_i32 s38, s3, s36
	s_add_i32 s5, s5, s38
.Lq_done_a:
	v_writelane_b32 v255, s39, 62
	v_mov_b32_e32 v164, s5

.LBB0_206:
	s_or_b64 exec, exec, s[0:1]
	v_readlane_b32 s0, v253, 27
	s_waitcnt lgkmcnt(0)
	s_barrier
	v_mov_b32_e32 v0, s0
	ds_read_b32 v0, v0
	v_readlane_b32 s0, v254, 25
	s_waitcnt lgkmcnt(0)
	v_readfirstlane_b32 s2, v0
	s_cmp_ge_i32 s2, s0
	s_cselect_b64 s[34:35], -1, 0
	s_and_b64 vcc, exec, s[34:35]
	s_cbranch_vccnz .LBB0_203
	s_mov_b64 s[0:1], exec
	v_readlane_b32 s4, v255, 27
	v_readlane_b32 s5, v255, 28
	s_and_b64 s[4:5], s[0:1], s[4:5]
	s_mov_b64 exec, s[4:5]
	s_cbranch_execz .LBB0_211
	s_getreg_b32 s3, hwreg(HW_REG_XCC_ID, 0, 4)
	s_and_b32 s3, s3, 7
	v_readlane_b32 s6, v255, 25
	v_readlane_b32 s7, v255, 26
	v_readlane_b32 s36, v255, 11
	v_readlane_b32 s37, v254, 25
	v_readlane_b32 s39, v255, 62
	s_mov_b32 s4, 8
	s_nop 4
